# v24: v23 + barriers that need no L2 write-back use one flat arrival counter (single atomic hop) instead of the per-XCC + top pair
# speedup vs baseline: 1.0056x; 1.0028x over previous
.LBB0_276:
	s_cmp_lt_i32 s59, 2
	s_barrier
	s_cbranch_scc1 .LBB0_330
	s_waitcnt vmcnt(0)
	s_barrier
	s_and_saveexec_b64 s[2:3], s[0:1]
	s_cbranch_execz .LBB0_329
	s_waitcnt vmcnt(0) lgkmcnt(0)
	v_mov_b32_e32 v241, 0
	v_lshlrev_b32_e64 v254, 8, s31
	v_mov_b32_e32 v247, 1
	v_add_u32_e32 v246, 0x1400, v254
	global_atomic_add v248, v246, v247, s[60:61] sc0
.Lxb0_top:
	ds_read_b128 v[242:245], v241
	s_waitcnt lgkmcnt(0)
	v_cmp_ne_u32_e32 vcc, 0, v242
	s_cbranch_vccz .Lxb0_census
.Lxb0_go:
	v_add_u32_e32 v249, 1, v244
	ds_write_b32 v241, v249 offset:8
	v_sub_u32_e32 v255, v249, v245
	v_mul_lo_u32 v250, v255, v242
	v_mul_lo_u32 v251, v255, v243
	v_add_u32_e32 v253, 0x2400, v254
	v_mov_b32_e32 v252, 0
	s_waitcnt vmcnt(0)
	buffer_inv sc1
	v_add_u32_e32 v248, 1, v248
	v_cmp_eq_u32_e32 vcc, v248, v250
	s_cbranch_vccz .Lxb0_wait
	buffer_wbl2 sc1
	s_waitcnt vmcnt(0)
	v_mov_b32_e32 v246, 0x3400
	global_atomic_add v248, v246, v247, s[60:61] sc0
	s_waitcnt vmcnt(0)
	v_add_u32_e32 v248, 1, v248
	v_cmp_ge_u32_e32 vcc, v248, v251
	s_cbranch_vccz .Lxb0_wait
	v_mov_b32_e32 v246, 0x2400
	global_atomic_add v246, v247, s[60:61]
	global_atomic_add v246, v247, s[60:61] offset:256
	global_atomic_add v246, v247, s[60:61] offset:512
	global_atomic_add v246, v247, s[60:61] offset:768
	global_atomic_add v246, v247, s[60:61] offset:1024
	global_atomic_add v246, v247, s[60:61] offset:1280
	global_atomic_add v246, v247, s[60:61] offset:1536
	global_atomic_add v246, v247, s[60:61] offset:1792
	global_atomic_add v246, v247, s[60:61] offset:2048
	global_atomic_add v246, v247, s[60:61] offset:2304
	global_atomic_add v246, v247, s[60:61] offset:2560
	global_atomic_add v246, v247, s[60:61] offset:2816
	global_atomic_add v246, v247, s[60:61] offset:3072
	global_atomic_add v246, v247, s[60:61] offset:3328
	global_atomic_add v246, v247, s[60:61] offset:3584
	global_atomic_add v246, v247, s[60:61] offset:3840
	s_branch .Lxb0_done

.Lxb0_top2:
	ds_read_b128 v[242:245], v241
	v_lshlrev_b32_e64 v254, 8, s31
	v_mov_b32_e32 v247, 1
	v_mov_b32_e32 v248, s99
	s_waitcnt lgkmcnt(0)
	s_branch .Lxb0_go

.LBB0_338:
	s_cmp_lt_i32 s59, 3
	s_barrier
	s_cbranch_scc1 .LBB0_392
	s_waitcnt vmcnt(0)
	s_barrier
	s_and_saveexec_b64 s[2:3], s[0:1]
	s_cbranch_execz .LBB0_391
	s_waitcnt vmcnt(0) lgkmcnt(0)
	v_mov_b32_e32 v241, 0
	v_lshlrev_b32_e64 v254, 8, s31
	v_mov_b32_e32 v247, 1
	v_add_u32_e32 v246, 0x1400, v254
	global_atomic_add v248, v246, v247, s[60:61] sc0

.LBB0_587:
	s_cmp_lt_i32 s59, 4
	s_waitcnt vmcnt(0)
	s_barrier
	s_cbranch_scc1 .LBB0_641
	s_waitcnt vmcnt(0)
	s_barrier
	s_and_saveexec_b64 s[2:3], s[0:1]
	s_cbranch_execz .LBB0_640
	s_waitcnt vmcnt(0) lgkmcnt(0)
	v_mov_b32_e32 v241, 0
	v_lshlrev_b32_e64 v254, 8, s31
	v_mov_b32_e32 v247, 1
	v_mov_b32_e32 v246, 0x3600
	global_atomic_add v248, v246, v247, s[60:61] sc0

.Lxb2_go:
	v_add_u32_e32 v249, 1, v244
	v_mov_b32_e32 v250, v249
	v_add_u32_e32 v251, 1, v245
	ds_write_b64 v241, v[250:251] offset:8
	v_mul_lo_u32 v251, v251, s56
	v_add_u32_e32 v253, 0x2400, v254
	v_mov_b32_e32 v252, 0
	s_waitcnt vmcnt(0)
	buffer_inv sc1
	v_add_u32_e32 v248, 1, v248
	v_cmp_eq_u32_e32 vcc, v248, v251
	s_cbranch_vccz .Lxb2_wait
	v_mov_b32_e32 v246, 0x2400
	global_atomic_add v246, v247, s[60:61]
	global_atomic_add v246, v247, s[60:61] offset:256
	global_atomic_add v246, v247, s[60:61] offset:512
	global_atomic_add v246, v247, s[60:61] offset:768
	global_atomic_add v246, v247, s[60:61] offset:1024
	global_atomic_add v246, v247, s[60:61] offset:1280
	global_atomic_add v246, v247, s[60:61] offset:1536
	global_atomic_add v246, v247, s[60:61] offset:1792
	global_atomic_add v246, v247, s[60:61] offset:2048
	global_atomic_add v246, v247, s[60:61] offset:2304
	global_atomic_add v246, v247, s[60:61] offset:2560
	global_atomic_add v246, v247, s[60:61] offset:2816
	global_atomic_add v246, v247, s[60:61] offset:3072
	global_atomic_add v246, v247, s[60:61] offset:3328
	global_atomic_add v246, v247, s[60:61] offset:3584
	global_atomic_add v246, v247, s[60:61] offset:3840
	s_branch .Lxb2_done

.LBB0_657:
	s_cmp_lt_i32 s59, 5
	s_barrier
	s_cbranch_scc1 .LBB0_711
	s_waitcnt vmcnt(0)
	s_barrier
	s_and_saveexec_b64 s[2:3], s[0:1]
	s_cbranch_execz .LBB0_710
	s_waitcnt vmcnt(0) lgkmcnt(0)
	v_mov_b32_e32 v241, 0
	v_lshlrev_b32_e64 v254, 8, s31
	v_mov_b32_e32 v247, 1
	v_add_u32_e32 v246, 0x1400, v254
	global_atomic_add v248, v246, v247, s[60:61] sc0

.LBB0_833:
	s_cmp_lt_i32 s59, 6
	s_waitcnt vmcnt(0)
	s_barrier
	s_cbranch_scc1 .LBB0_887
	s_waitcnt vmcnt(0)
	s_barrier
	s_and_saveexec_b64 s[2:3], s[0:1]
	s_cbranch_execz .LBB0_886
	s_waitcnt vmcnt(0) lgkmcnt(0)
	v_mov_b32_e32 v241, 0
	v_lshlrev_b32_e64 v254, 8, s31
	v_mov_b32_e32 v247, 1
	v_add_u32_e32 v246, 0x1400, v254
	global_atomic_add v248, v246, v247, s[60:61] sc0

.LBB0_986:
	s_cmp_lt_i32 s59, 7
	s_barrier
	s_cbranch_scc1 .LBB0_1040
	s_waitcnt vmcnt(0)
	s_barrier
	s_and_saveexec_b64 s[2:3], s[0:1]
	s_cbranch_execz .LBB0_1039
	s_waitcnt vmcnt(0) lgkmcnt(0)
	v_mov_b32_e32 v241, 0
	v_lshlrev_b32_e64 v254, 8, s31
	v_mov_b32_e32 v247, 1
	v_add_u32_e32 v246, 0x1400, v254
	global_atomic_add v248, v246, v247, s[60:61] sc0

.LBB0_1106:
	s_cmp_lt_i32 s59, 8
	s_barrier
	s_cbranch_scc1 .LBB0_1160
	s_waitcnt vmcnt(0)
	s_barrier
	s_and_saveexec_b64 s[2:3], s[0:1]
	s_cbranch_execz .LBB0_1159
	s_waitcnt vmcnt(0) lgkmcnt(0)
	v_mov_b32_e32 v241, 0
	v_lshlrev_b32_e64 v254, 8, s31
	v_mov_b32_e32 v247, 1
	v_add_u32_e32 v246, 0x1400, v254
	global_atomic_add v248, v246, v247, s[60:61] sc0

.LBB0_1285:
	s_cmp_lt_i32 s59, 10
	s_waitcnt vmcnt(0)
	s_barrier
	s_cbranch_scc1 .LBB0_1339
	s_waitcnt vmcnt(0)
	s_barrier
	s_and_saveexec_b64 s[2:3], s[0:1]
	s_cbranch_execz .LBB0_1338
	s_waitcnt vmcnt(0) lgkmcnt(0)
	v_mov_b32_e32 v241, 0
	v_lshlrev_b32_e64 v254, 8, s31
	v_mov_b32_e32 v247, 1
	v_mov_b32_e32 v246, 0x3600
	global_atomic_add v248, v246, v247, s[60:61] sc0

.LBB0_1347:
	s_cmp_lt_i32 s59, 11
	s_barrier
	s_cbranch_scc1 .LBB0_1401
	s_waitcnt vmcnt(0)
	s_barrier
	s_and_saveexec_b64 s[2:3], s[0:1]
	s_cbranch_execz .LBB0_1400
	s_waitcnt vmcnt(0) lgkmcnt(0)
	v_mov_b32_e32 v241, 0
	v_lshlrev_b32_e64 v254, 8, s31
	v_mov_b32_e32 v247, 1
	v_add_u32_e32 v246, 0x1400, v254
	global_atomic_add v248, v246, v247, s[60:61] sc0

.Lcv4_2:
.LBB0_1558:
	s_cmp_lt_i32 s59, 12
	s_waitcnt lgkmcnt(0)
	s_barrier
	s_cbranch_scc1 .LBB0_1612
	s_waitcnt vmcnt(0)
	s_barrier
	s_and_saveexec_b64 s[2:3], s[0:1]
	s_cbranch_execz .LBB0_1611
	s_waitcnt vmcnt(0) lgkmcnt(0)
	v_mov_b32_e32 v241, 0
	v_lshlrev_b32_e64 v254, 8, s31
	v_mov_b32_e32 v247, 1
	v_mov_b32_e32 v246, 0x3600
	global_atomic_add v248, v246, v247, s[60:61] sc0

.LBB0_2400:
	s_cmp_lt_i32 s59, 14
	s_waitcnt vmcnt(0)
	s_barrier
	s_cbranch_scc1 .LBB0_2454
	s_waitcnt vmcnt(0)
	s_barrier
	s_and_saveexec_b64 s[2:3], s[0:1]
	s_cbranch_execz .LBB0_2453
	s_waitcnt vmcnt(0) lgkmcnt(0)
	v_mov_b32_e32 v241, 0
	v_lshlrev_b32_e64 v254, 8, s31
	v_mov_b32_e32 v247, 1
	v_mov_b32_e32 v246, 0x3600
	global_atomic_add v248, v246, v247, s[60:61] sc0

.LBB0_2462:
	s_cmp_lt_i32 s59, 15
	s_barrier
	s_cbranch_scc1 .LBB0_2516
	s_waitcnt vmcnt(0)
	s_barrier
	s_and_saveexec_b64 s[2:3], s[0:1]
	s_cbranch_execz .LBB0_2515
	s_waitcnt vmcnt(0) lgkmcnt(0)
	v_mov_b32_e32 v241, 0
	v_lshlrev_b32_e64 v254, 8, s31
	v_mov_b32_e32 v247, 1
	v_add_u32_e32 v246, 0x1400, v254
	global_atomic_add v248, v246, v247, s[60:61] sc0

.LBB0_2579:
	s_cmp_lt_i32 s59, 16
	s_waitcnt vmcnt(0)
	s_barrier
	s_cbranch_scc1 .LBB0_2634
	s_waitcnt vmcnt(0)
	s_barrier
	s_and_saveexec_b64 s[2:3], s[0:1]
	s_cbranch_execz .LBB0_2633
	s_waitcnt vmcnt(0) lgkmcnt(0)
	v_mov_b32_e32 v241, 0
	v_lshlrev_b32_e64 v254, 8, s31
	v_mov_b32_e32 v247, 1
	v_mov_b32_e32 v246, 0x3600
	global_atomic_add v248, v246, v247, s[60:61] sc0

.LBB0_2702:
	s_cmp_lt_i32 s59, 17
	s_barrier
	s_cbranch_scc1 .LBB0_2756
	s_waitcnt vmcnt(0)
	s_barrier
	s_and_saveexec_b64 s[2:3], s[0:1]
	s_cbranch_execz .LBB0_2755
	s_waitcnt vmcnt(0) lgkmcnt(0)
	v_mov_b32_e32 v241, 0
	v_lshlrev_b32_e64 v254, 8, s31
	v_mov_b32_e32 v247, 1
	v_add_u32_e32 v246, 0x1400, v254
	global_atomic_add v248, v246, v247, s[60:61] sc0

.LBB0_2844:
	s_cmp_lt_i32 s59, 18
	s_barrier
	s_cbranch_scc1 .LBB0_2898
	s_waitcnt vmcnt(0)
	s_barrier
	s_and_saveexec_b64 s[2:3], s[0:1]
	s_cbranch_execz .LBB0_2897
	s_waitcnt vmcnt(0) lgkmcnt(0)
	v_mov_b32_e32 v241, 0
	v_lshlrev_b32_e64 v254, 8, s31
	v_mov_b32_e32 v247, 1
	v_add_u32_e32 v246, 0x1400, v254
	global_atomic_add v248, v246, v247, s[60:61] sc0

.LBB0_3024:
	s_cmp_lt_i32 s59, 20
	s_waitcnt vmcnt(0)
	s_barrier
	s_cbranch_scc1 .LBB0_3078
	s_waitcnt vmcnt(0)
	s_barrier
	s_and_saveexec_b64 s[2:3], s[0:1]
	s_cbranch_execz .LBB0_3077
	s_waitcnt vmcnt(0) lgkmcnt(0)
	v_mov_b32_e32 v241, 0
	v_lshlrev_b32_e64 v254, 8, s31
	v_mov_b32_e32 v247, 1
	v_add_u32_e32 v246, 0x1400, v254
	global_atomic_add v248, v246, v247, s[60:61] sc0

.LBB0_3082:
	s_cmp_lt_u32 s59, 21
	s_barrier
	s_cbranch_scc1 .LBB0_3136
	s_waitcnt vmcnt(0)
	s_barrier
	s_and_saveexec_b64 s[2:3], s[0:1]
	s_cbranch_execz .LBB0_3135
	s_waitcnt vmcnt(0) lgkmcnt(0)
	v_mov_b32_e32 v241, 0
	v_lshlrev_b32_e64 v254, 8, s31
	v_mov_b32_e32 v247, 1
	v_mov_b32_e32 v246, 0x3600
	global_atomic_add v248, v246, v247, s[60:61] sc0

.LBB0_3155:
	s_cmp_lt_i32 s59, 22
	s_waitcnt vmcnt(0)
	s_barrier
	s_cbranch_scc1 .LBB0_3209
	s_waitcnt vmcnt(0)
	s_barrier
	s_and_saveexec_b64 s[2:3], s[0:1]
	s_cbranch_execz .LBB0_3208
	s_waitcnt vmcnt(0) lgkmcnt(0)
	v_mov_b32_e32 v241, 0
	v_lshlrev_b32_e64 v254, 8, s31
	v_mov_b32_e32 v247, 1
	v_mov_b32_e32 v246, 0x3600
	global_atomic_add v248, v246, v247, s[60:61] sc0

.LBB0_3217:
	s_cmp_lt_i32 s59, 23
	s_barrier
	s_cbranch_scc1 .LBB0_3271
	s_waitcnt vmcnt(0)
	s_barrier
	s_and_saveexec_b64 s[2:3], s[0:1]
	s_cbranch_execz .LBB0_3270
	s_waitcnt vmcnt(0) lgkmcnt(0)
	v_mov_b32_e32 v241, 0
	v_lshlrev_b32_e64 v254, 8, s31
	v_mov_b32_e32 v247, 1
	v_add_u32_e32 v246, 0x1400, v254
	global_atomic_add v248, v246, v247, s[60:61] sc0

.LBB0_3341:
	s_cmp_lt_i32 s59, 24
	s_waitcnt lgkmcnt(0)
	s_barrier
	s_cbranch_scc1 .LBB0_3395
	s_waitcnt vmcnt(0)
	s_barrier
	s_and_saveexec_b64 s[2:3], s[0:1]
	s_cbranch_execz .LBB0_3394
	s_waitcnt vmcnt(0) lgkmcnt(0)
	v_mov_b32_e32 v241, 0
	v_lshlrev_b32_e64 v254, 8, s31
	v_mov_b32_e32 v247, 1
	v_mov_b32_e32 v246, 0x3600
	global_atomic_add v248, v246, v247, s[60:61] sc0

.LBB0_3517:
	s_cmp_lt_i32 s59, 26
	s_waitcnt vmcnt(0)
	s_barrier
	s_cbranch_scc1 .LBB0_3571
	s_waitcnt vmcnt(0)
	s_barrier
	s_and_saveexec_b64 s[2:3], s[0:1]
	s_cbranch_execz .LBB0_3570
	s_waitcnt vmcnt(0) lgkmcnt(0)
	v_mov_b32_e32 v241, 0
	v_lshlrev_b32_e64 v254, 8, s31
	v_mov_b32_e32 v247, 1
	v_mov_b32_e32 v246, 0x3600
	global_atomic_add v248, v246, v247, s[60:61] sc0
